# GEMM unit preheader: accumulators zeroed with 64 v_mov_b64 instead of 128 v_mov_b32, full drain after the zeroing
# speedup vs baseline: 1.0091x; 1.0091x over previous
; template <class Epi, class Sched, bool ALIGN_EPI = false, bool SP2 = false>
; __device__ __forceinline__ void gemm_phase(PG8_LAS unsigned char* lds, const Gemm g, const Sched& S, const Epi& E) {
;     ...
; #pragma unroll
;         for (int a = 0; a < 2; ++a)
; #pragma unroll
;             for (int b = 0; b < 2; ++b)
; #pragma unroll
;                 for (int m = 0; m < 4; ++m)
; #pragma unroll
;                     for (int n = 0; n < 2; ++n) acc[a][b][m][n] = (f32x4){0.f, 0.f, 0.f, 0.f};
;         cur = nxt; cA = nA; cB = nB; ++ui;
.LBB0_161:
	s_add_u32 s25, s10, s21
	s_addc_u32 s26, s11, 0
	s_mov_b64 s[12:13], 0
	v_mov_b64_e32 v[0:1], 0
	v_mov_b64_e32 v[2:3], 0
	v_mov_b64_e32 v[4:5], 0
	v_mov_b64_e32 v[6:7], 0
	v_mov_b64_e32 v[8:9], 0
	v_mov_b64_e32 v[10:11], 0
	v_mov_b64_e32 v[12:13], 0
	v_mov_b64_e32 v[14:15], 0
	v_mov_b64_e32 v[16:17], 0
	v_mov_b64_e32 v[18:19], 0
	v_mov_b64_e32 v[20:21], 0
	v_mov_b64_e32 v[22:23], 0
	v_mov_b64_e32 v[24:25], 0
	v_mov_b64_e32 v[26:27], 0
	v_mov_b64_e32 v[28:29], 0
	v_mov_b64_e32 v[30:31], 0
	v_mov_b64_e32 v[32:33], 0
	v_mov_b64_e32 v[34:35], 0
	v_mov_b64_e32 v[36:37], 0
	v_mov_b64_e32 v[38:39], 0
	v_mov_b64_e32 v[40:41], 0
	v_mov_b64_e32 v[42:43], 0
	v_mov_b64_e32 v[44:45], 0
	v_mov_b64_e32 v[46:47], 0
	v_mov_b64_e32 v[48:49], 0
	v_mov_b64_e32 v[50:51], 0
	v_mov_b64_e32 v[52:53], 0
	v_mov_b64_e32 v[54:55], 0
	v_mov_b64_e32 v[56:57], 0
	v_mov_b64_e32 v[58:59], 0
	v_mov_b64_e32 v[60:61], 0
	v_mov_b64_e32 v[62:63], 0
	v_mov_b64_e32 v[64:65], 0
	v_mov_b64_e32 v[66:67], 0
	v_mov_b64_e32 v[68:69], 0
	v_mov_b64_e32 v[70:71], 0
	v_mov_b64_e32 v[72:73], 0
	v_mov_b64_e32 v[74:75], 0
	v_mov_b64_e32 v[76:77], 0
	v_mov_b64_e32 v[78:79], 0
	v_mov_b64_e32 v[80:81], 0
	v_mov_b64_e32 v[82:83], 0
	v_mov_b64_e32 v[84:85], 0
	v_mov_b64_e32 v[86:87], 0
	v_mov_b64_e32 v[88:89], 0
	v_mov_b64_e32 v[90:91], 0
	v_mov_b64_e32 v[92:93], 0
	v_mov_b64_e32 v[94:95], 0
	v_mov_b64_e32 v[96:97], 0
	v_mov_b64_e32 v[98:99], 0
	v_mov_b64_e32 v[100:101], 0
	v_mov_b64_e32 v[102:103], 0
	v_mov_b64_e32 v[104:105], 0
	v_mov_b64_e32 v[106:107], 0
	v_mov_b64_e32 v[108:109], 0
	v_mov_b64_e32 v[110:111], 0
	v_mov_b64_e32 v[112:113], 0
	v_mov_b64_e32 v[114:115], 0
	v_mov_b64_e32 v[116:117], 0
	v_mov_b64_e32 v[118:119], 0
	v_mov_b64_e32 v[120:121], 0
	v_mov_b64_e32 v[122:123], 0
	v_mov_b64_e32 v[124:125], 0
	v_mov_b64_e32 v[126:127], 0
	s_waitcnt vmcnt(0)
	s_and_b64 vcc, exec, s[86:87]
	s_cbranch_vccnz .Lsp_skip
	s_setprio 1
